# dilated items hand the Y-pass partial numerators/denominators to the X pass through LDS (two half exchanges) instead of a global f32 scratch round trip
# speedup vs baseline: 1.0162x; 1.0162x over previous
; __global__ void __launch_bounds__(NTHREADS) fwd_megakernel(Params P) {
;     ...
;             if (rep == 0 || NREP(7) == 2) {
;                 for (int it = 512 + bid; it < 1024; it += G) {
;                     P2_DECODE(it);
;                     attn_a_y(ws, buf, bh, sub * 512 + wid * 64, lane);
;                     __syncthreads();
;                     attn_a_x(ws, buf, bh, wid, sub * 32, lane);
.LBB0_591:
	s_barrier
	s_add_i32 s1, s3, 0x200
	s_and_b32 s18, s30, 0xffffffc0
	v_mov_b32_e32 v183, 0
	v_lshlrev_b32_e32 v0, 2, v186
	v_mov_b32_e32 v1, v183
	s_add_u32 s2, s50, 0x1a000000
	v_lshl_add_u64 v[176:177], s[54:55], 0, v[0:1]
	s_addc_u32 s19, s51, 0
	v_lshlrev_b32_e32 v0, 1, v186
	s_lshl_b32 s6, s30, 7
	v_lshl_add_u64 v[178:179], s[60:61], 0, v[0:1]
	v_lshl_add_u64 v[184:185], s[26:27], 0, v[0:1]
	v_lshlrev_b32_e32 v0, 2, v180
	s_and_b32 s6, s6, 0xffffe000
	v_sub_u32_e32 v198, 0, v0
	v_or_b32_e32 v0, s6, v231
	s_movk_i32 s6, 0xd000
	v_readlane_b32 s96, v255, 8
	s_movk_i32 s0, 0x200
	v_lshl_or_b32 v181, v219, 11, v216
	v_lshl_or_b32 v193, v218, 11, v216
	v_lshl_or_b32 v194, v217, 11, v216
	v_lshl_or_b32 v195, v215, 11, v216
	v_lshlrev_b32_e32 v196, 6, v180
	v_or_b32_e32 v197, s23, v220
	s_mov_b32 s9, 0
	v_add_u32_e32 v199, 0x61, v214
	v_add3_u32 v200, v0, v216, s6
	s_movk_i32 s20, 0x80
	s_movk_i32 s21, 0x800
	s_movk_i32 s30, 0x81
	s_movk_i32 s31, 0xff7e
	s_movk_i32 s33, 0x801
	s_movk_i32 s60, 0xf7fe
	s_movk_i32 s61, 0x201
	s_movk_i32 s62, 0xfdfe
	v_mov_b32_e32 v201, 0xf149f2ca
	v_readlane_b32 s97, v255, 9
	v_readlane_b32 s90, v255, 7
	s_branch .LBB0_593

; DI void attn_a_y(unsigned char* ws, LAS unsigned char* buf, int bh, int t0, int lane) {
;     ...
;     const float la = a.st.l + __shfl_xor(a.st.l, 32), lb = b.st.l + __shfl_xor(b.st.l, 32);
;     float* exa = (float*)(ws + WS_EXO) + ((size_t)bh * SEQ + qpa) * 64 + 4 * h;
;     float* exb = exa + 32 * 64;
; #pragma unroll
;     for (int g = 0; g < 4; ++g) {
;         *(f32x4*)(exa + 8 * g) = (f32x4){a.st.o0[4 * g], a.st.o0[4 * g + 1], a.st.o0[4 * g + 2], a.st.o0[4 * g + 3]};
;         *(f32x4*)(exa + 32 + 8 * g) = (f32x4){a.st.o1[4 * g], a.st.o1[4 * g + 1], a.st.o1[4 * g + 2], a.st.o1[4 * g + 3]};
;         *(f32x4*)(exb + 8 * g) = (f32x4){b.st.o0[4 * g], b.st.o0[4 * g + 1], b.st.o0[4 * g + 2], b.st.o0[4 * g + 3]};
;         *(f32x4*)(exb + 32 + 8 * g) = (f32x4){b.st.o1[4 * g], b.st.o1[4 * g + 1], b.st.o1[4 * g + 2], b.st.o1[4 * g + 3]};
;     }
;     if (h == 0) { float* exl = (float*)(ws + WS_EXL) + (size_t)bh * SEQ; exl[qpa] = la; exl[qpb] = lb; }
; DI void attn_a_x(unsigned char* ws, LAS unsigned char* buf, int bh, int ra, int i0, int lane) {
;     ...
;     {
;         const float* exa = (const float*)(ws + WS_EXO) + ((size_t)bh * SEQ + qpa) * 64 + 4 * h;
;         const float* exb = exa + 8 * 64;
; #pragma unroll
;         for (int g = 0; g < 4; ++g) {
;             const f32x4 a0 = *(const f32x4*)(exa + 8 * g), a1 = *(const f32x4*)(exa + 32 + 8 * g), b0 = *(const f32x4*)(exb + 8 * g), b1 = *(const f32x4*)(exb + 32 + 8 * g);
; #pragma unroll
;             for (int j = 0; j < 4; ++j) { a.st.o0[4 * g + j] = a0[j]; a.st.o1[4 * g + j] = a1[j]; b.st.o0[4 * g + j] = b0[j]; b.st.o1[4 * g + j] = b1[j]; }
;         }
;         const float* exl = (const float*)(ws + WS_EXL) + (size_t)bh * SEQ;
;         a.st.l = (h == 0) ? exl[qpa] : 0.f; b.st.l = (h == 0) ? exl[qpb] : 0.f;
;     }
.LBB0_601:
	ds_bpermute_b32 v64, v191, v189
	ds_bpermute_b32 v65, v191, v188
	v_and_b32_e32 v66, 7, v234
	v_lshlrev_b32_e32 v66, 5, v66
	v_lshrrev_b32_e32 v67, 6, v234
	v_lshl_add_u32 v66, v67, 2, v66
	v_bfe_u32 v80, v234, 4, 1
	v_add_u32_e32 v66, v66, v80
	v_mul_u32_u24_e32 v66, 0x110, v66
	v_bfe_u32 v80, v234, 5, 1
	v_lshlrev_b32_e32 v80, 4, v80
	v_add_u32_e32 v66, v66, v80
	v_add_u32_e32 v66, 0x12000, v66
	v_lshlrev_b32_e32 v67, 5, v67
	v_and_b32_e32 v68, 31, v234
	v_add_u32_e32 v67, v67, v68
	v_mul_u32_u24_e32 v67, 0x110, v67
	v_add_u32_e32 v67, v67, v80
	v_add_u32_e32 v67, 0x12000, v67
	s_waitcnt lgkmcnt(0)
	v_add_f32_e32 v64, v189, v64
	v_add_f32_e32 v65, v188, v65
	s_mov_b32 exec_lo, 0xff00ff
	s_mov_b32 exec_hi, 0xff00ff
	ds_write_b128 v66, v[32:35] offset:0
	ds_write_b128 v66, v[36:39] offset:32
	ds_write_b128 v66, v[40:43] offset:64
	ds_write_b128 v66, v[44:47] offset:96
	ds_write_b128 v66, v[48:51] offset:128
	ds_write_b128 v66, v[52:55] offset:160
	ds_write_b128 v66, v[56:59] offset:192
	ds_write_b128 v66, v[60:63] offset:224
	ds_write_b128 v66, v[16:19] offset:544
	ds_write_b128 v66, v[20:23] offset:576
	ds_write_b128 v66, v[24:27] offset:608
	ds_write_b128 v66, v[28:31] offset:640
	ds_write_b128 v66, v[0:3] offset:672
	ds_write_b128 v66, v[4:7] offset:704
	ds_write_b128 v66, v[8:11] offset:736
	ds_write_b128 v66, v[12:15] offset:768
	s_mov_b32 exec_hi, 0
	ds_write_b32 v66, v64 offset:256
	ds_write_b32 v66, v65 offset:800
	s_mov_b64 exec, -1
	s_waitcnt lgkmcnt(0)
	s_barrier
	ds_read_b128 v[144:147], v67 offset:0
	ds_read_b128 v[148:151], v67 offset:32
	ds_read_b128 v[152:155], v67 offset:64
	ds_read_b128 v[156:159], v67 offset:96
	ds_read_b128 v[160:163], v67 offset:128
	ds_read_b128 v[164:167], v67 offset:160
	ds_read_b128 v[168:171], v67 offset:192
	ds_read_b128 v[172:175], v67 offset:224
	v_mov_b32_e32 v68, 0
	s_mov_b32 exec_hi, 0
	ds_read_b32 v68, v67 offset:256
	s_mov_b64 exec, -1
	s_waitcnt lgkmcnt(0)
	s_barrier
	s_mov_b32 exec_lo, 0xff00ff00
	s_mov_b32 exec_hi, 0xff00ff00
	ds_write_b128 v66, v[32:35] offset:0
	ds_write_b128 v66, v[36:39] offset:32
	ds_write_b128 v66, v[40:43] offset:64
	ds_write_b128 v66, v[44:47] offset:96
	ds_write_b128 v66, v[48:51] offset:128
	ds_write_b128 v66, v[52:55] offset:160
	ds_write_b128 v66, v[56:59] offset:192
	ds_write_b128 v66, v[60:63] offset:224
	ds_write_b128 v66, v[16:19] offset:544
	ds_write_b128 v66, v[20:23] offset:576
	ds_write_b128 v66, v[24:27] offset:608
	ds_write_b128 v66, v[28:31] offset:640
	ds_write_b128 v66, v[0:3] offset:672
	ds_write_b128 v66, v[4:7] offset:704
	ds_write_b128 v66, v[8:11] offset:736
	ds_write_b128 v66, v[12:15] offset:768
	s_mov_b32 exec_hi, 0
	ds_write_b32 v66, v64 offset:256
	ds_write_b32 v66, v65 offset:800
	s_mov_b64 exec, -1
	s_waitcnt lgkmcnt(0)
	s_barrier
.LBB0_603:
	s_lshl_b32 s16, s56, 5
	v_or_b32_e32 v0, s16, v214
	v_lshlrev_b32_e32 v81, 4, v0
	v_add_u32_e32 v186, s22, v81
	v_ashrrev_i32_e32 v187, 31, v186
	v_lshlrev_b64 v[0:1], 7, v[186:187]
	v_add_u32_e32 v188, 8, v186
	v_lshl_add_u64 v[0:1], s[14:15], 0, v[0:1]
	v_lshl_add_u64 v[0:1], v[0:1], 0, v[182:183]
	v_ashrrev_i32_e32 v189, 31, v188
	s_waitcnt lgkmcnt(0)
	global_load_dword v80, v183, s[68:69]
	global_load_dwordx4 v[136:139], v[0:1], off
	global_load_dwordx4 v[128:131], v[0:1], off offset:32
	global_load_dwordx4 v[124:127], v[0:1], off offset:64
	global_load_dwordx4 v[112:115], v[0:1], off offset:96
	v_lshlrev_b64 v[0:1], 7, v[188:189]
	v_lshl_add_u64 v[0:1], s[14:15], 0, v[0:1]
	v_lshl_add_u64 v[0:1], v[0:1], 0, v[182:183]
	global_load_dwordx4 v[140:143], v[0:1], off
	global_load_dwordx4 v[132:135], v[0:1], off offset:32
	global_load_dwordx4 v[120:123], v[0:1], off offset:64
	global_load_dwordx4 v[116:119], v[0:1], off offset:96
	ds_read_b128 v[16:19], v67 offset:0
	ds_read_b128 v[20:23], v67 offset:32
	ds_read_b128 v[24:27], v67 offset:64
	ds_read_b128 v[28:31], v67 offset:96
	ds_read_b128 v[0:3], v67 offset:128
	ds_read_b128 v[4:7], v67 offset:160
	ds_read_b128 v[8:11], v67 offset:192
	ds_read_b128 v[12:15], v67 offset:224
	v_mov_b32_e32 v202, 0
	s_mov_b32 exec_hi, 0
	ds_read_b32 v202, v67 offset:256
	s_mov_b64 exec, -1
	v_mov_b32_e32 v203, v68
	v_mov_b32_e32 v48, v144
	v_mov_b32_e32 v49, v145
	v_mov_b32_e32 v50, v146
	v_mov_b32_e32 v51, v147
	v_mov_b32_e32 v52, v148
	v_mov_b32_e32 v53, v149
	v_mov_b32_e32 v54, v150
	v_mov_b32_e32 v55, v151
	v_mov_b32_e32 v56, v152
	v_mov_b32_e32 v57, v153
	v_mov_b32_e32 v58, v154
	v_mov_b32_e32 v59, v155
	v_mov_b32_e32 v60, v156
	v_mov_b32_e32 v61, v157
	v_mov_b32_e32 v62, v158
	v_mov_b32_e32 v63, v159
	v_mov_b32_e32 v32, v160
	v_mov_b32_e32 v33, v161
	v_mov_b32_e32 v34, v162
	v_mov_b32_e32 v35, v163
	v_mov_b32_e32 v36, v164
	v_mov_b32_e32 v37, v165
	v_mov_b32_e32 v38, v166
	v_mov_b32_e32 v39, v167
	v_mov_b32_e32 v40, v168
	v_mov_b32_e32 v41, v169
	v_mov_b32_e32 v42, v170
	v_mov_b32_e32 v43, v171
	v_mov_b32_e32 v44, v172
	v_mov_b32_e32 v45, v173
	v_mov_b32_e32 v46, v174
	v_mov_b32_e32 v47, v175
	s_waitcnt lgkmcnt(0)
	s_barrier
	s_cmp_gt_u32 s56, 3
	s_mov_b32 s63, 0
	s_cbranch_scc1 .LBB0_610
